# speedup vs baseline: 1.0124x; 1.0081x over previous
; __device__ __forceinline__ float silu_f(float x) { return x * __builtin_amdgcn_rcpf(1.f + __expf(-x)); }
; __device__ __forceinline__ void norm_fix(f32x4 (&acc)[4][4], const float* rowss, const float* shW, int N, int brow, int bcol,
;                                          int wr, int wc, int fr, int fq) {
;   int mr = brow >> 12;
;   float sw[4];
; #pragma unroll
;   for (int n = 0; n < 4; n++) sw[n] = shW[(size_t)mr * N + bcol + (n >> 1) * 128 + wc * 32 + (n & 1) * 16 + fr];
; #pragma unroll
;   for (int m = 0; m < 4; m++)
; #pragma unroll
;     for (int j = 0; j < 4; j++) {
;       float rs = rsqrtf(rowss[brow + wr * 64 + m * 16 + fq * 4 + j] * (1.f / D) + 1e-6f);
; #pragma unroll
;       for (int n = 0; n < 4; n++) acc[m][n][j] = acc[m][n][j] * rs + sw[n];
;     }
; }
;   __device__ __forceinline__ void operator()(int brow, int bcol, int wr, int wc, int fr, int fq, f32x4 (&acc)[4][4], int split) const {
;     if (rowss && brow < TL) norm_fix(acc, rowss, shW, NGU, brow, bcol, wr, wc, fr, fq);
; #pragma unroll
;     for (int m = 0; m < 4; m++)
; #pragma unroll
;       for (int pr = 0; pr < 2; pr++)
; #pragma unroll
;         for (int j = 0; j < 4; j++) {
;           int row = brow + wr * 64 + m * 16 + fq * 4 + j;
;           int col = (bcol >> 1) + wc * 32 + pr * 16 + fr;
;           float g = acc[m][2 * pr][j], u = acc[m][2 * pr + 1][j];
;           act[(size_t)row * DFF + col] = f2bf(silu_f(g) * u);
.LBB0_1322:
	s_ashr_i32 s0, s58, 1
	v_add_u32_e32 v140, s0, v144
	s_ashr_i32 s0, s4, 12
	s_ashr_i32 s59, s58, 31
	s_mul_hi_i32 s1, s0, 0x5800
	s_mulk_i32 s0, 0x5800
	s_add_u32 s0, s33, s0
	s_addc_u32 s1, s45, s1
	s_lshl_b64 s[58:59], s[58:59], 2
	s_add_u32 s0, s0, s58
	s_addc_u32 s1, s1, s59
	v_add_u32_e32 v138, s4, v145
	s_add_u32 s0, s0, s92
	v_ashrrev_i32_e32 v139, 31, v138
	s_addc_u32 s1, s1, 0
	v_lshl_add_u64 v[136:137], v[138:139], 2, s[76:77]
	global_load_dword v150, v146, s[0:1]
	global_load_dword v151, v146, s[0:1] offset:64
	global_load_dword v148, v146, s[0:1] offset:512
	global_load_dword v149, v146, s[0:1] offset:576
	global_load_dwordx4 v[184:187], v[136:137], off offset:64
	global_load_dwordx4 v[188:191], v[136:137], off offset:128
	global_load_dwordx4 v[192:195], v[136:137], off offset:192
	global_load_dwordx4 v[160:163], v[136:137], off
	v_mov_b64_e32 v[136:137], s[46:47]
	v_readlane_b32 s60, v255, 10
	v_ashrrev_i32_e32 v141, 31, v140
	v_readlane_b32 s66, v255, 16
	v_readlane_b32 s67, v255, 17
	v_readlane_b32 s61, v255, 11
	v_readlane_b32 s62, v255, 12
	v_readlane_b32 s63, v255, 13
	v_readlane_b32 s64, v255, 14
	v_readlane_b32 s65, v255, 15
	v_readlane_b32 s68, v255, 18
	v_readlane_b32 s69, v255, 19
	v_readlane_b32 s70, v255, 20
	v_readlane_b32 s71, v255, 21
	v_readlane_b32 s72, v255, 22
	v_readlane_b32 s73, v255, 23
	v_readlane_b32 s74, v255, 24
	v_readlane_b32 s75, v255, 25
	s_waitcnt vmcnt(0)
	v_pk_fma_f32 v[152:153], v[160:161], s[44:45], v[136:137] op_sel_hi:[1,0,0]
	s_nop 0
	v_mul_f32_e32 v139, 0x4b800000, v152
	v_cmp_gt_f32_e64 s[4:5], s93, v152
	v_cmp_gt_f32_e32 vcc, s93, v153
	s_nop 0
	v_cndmask_b32_e64 v139, v152, v139, s[4:5]
	v_rsq_f32_e32 v139, v139
	s_nop 0
	v_mul_f32_e32 v152, 0x45800000, v139
	v_cndmask_b32_e64 v152, v139, v152, s[4:5]
	v_fma_f32 v159, v112, v152, v150
	v_mul_f32_e32 v112, 0x4b800000, v153
	v_cndmask_b32_e32 v112, v153, v112, vcc
	v_rsq_f32_e32 v112, v112
	v_fma_f32 v160, v116, v152, v151
	v_fma_f32 v139, v120, v152, v148
	v_fma_f32 v152, v124, v152, v149
	v_mul_f32_e32 v116, 0x45800000, v112
	v_cndmask_b32_e32 v112, v112, v116, vcc
	v_fma_f32 v155, v113, v112, v150
	v_fma_f32 v156, v117, v112, v151
	v_fma_f32 v121, v121, v112, v148
	v_fma_f32 v124, v125, v112, v149
	v_pk_fma_f32 v[112:113], v[162:163], s[44:45], v[136:137] op_sel_hi:[1,0,0]
	s_nop 0
	v_mul_f32_e32 v116, 0x4b800000, v112
	v_cmp_gt_f32_e64 s[4:5], s93, v112
	v_cmp_gt_f32_e32 vcc, s93, v113
	s_nop 0
	v_cndmask_b32_e64 v112, v112, v116, s[4:5]
	v_rsq_f32_e32 v112, v112
	s_nop 0
	v_mul_f32_e32 v116, 0x45800000, v112
	v_cndmask_b32_e64 v112, v112, v116, s[4:5]
	v_fma_f32 v153, v114, v112, v150
	v_fma_f32 v154, v118, v112, v151
	v_fma_f32 v118, v122, v112, v148
	v_fma_f32 v120, v126, v112, v149
	v_mul_f32_e32 v112, 0x4b800000, v113
	v_cndmask_b32_e32 v112, v113, v112, vcc
	v_rsq_f32_e32 v112, v112
	s_nop 0
	v_mul_f32_e32 v113, 0x45800000, v112
	v_cndmask_b32_e32 v112, v112, v113, vcc
	v_fma_f32 v122, v115, v112, v150
	v_fma_f32 v119, v119, v112, v151
	v_fma_f32 v116, v123, v112, v148
	v_fma_f32 v117, v127, v112, v149
	v_add_u32_e32 v112, 16, v138
	v_ashrrev_i32_e32 v113, 31, v112
	v_lshl_add_u64 v[114:115], v[112:113], 2, s[76:77]
	v_mov_b32_e32 v113, v184
	s_waitcnt vmcnt(0)
	v_fmamk_f32 v113, v113, 0x3a800000, v147
	v_cmp_gt_f32_e32 vcc, s93, v113
	v_mul_f32_e32 v114, 0x4b800000, v113
	s_nop 0
	v_cndmask_b32_e32 v113, v113, v114, vcc
	v_rsq_f32_e32 v113, v113
	s_nop 0
	v_mul_f32_e32 v114, 0x45800000, v113
	v_cndmask_b32_e32 v114, v113, v114, vcc
	v_fma_f32 v123, v96, v114, v150
	v_fma_f32 v125, v100, v114, v151
	v_fma_f32 v113, v104, v114, v148
	v_fma_f32 v108, v108, v114, v149
	v_add_u32_e32 v114, 17, v138
	v_ashrrev_i32_e32 v115, 31, v114
	v_lshl_add_u64 v[126:127], v[114:115], 2, s[76:77]
	v_mov_b32_e32 v96, v185
	v_add_u32_e32 v104, 19, v138
	s_waitcnt vmcnt(0)
	v_fmamk_f32 v96, v96, 0x3a800000, v147
	v_cmp_gt_f32_e32 vcc, s93, v96
	v_mul_f32_e32 v100, 0x4b800000, v96
	s_nop 0
	v_cndmask_b32_e32 v96, v96, v100, vcc
	v_rsq_f32_e32 v96, v96
	s_nop 0
	v_mul_f32_e32 v100, 0x45800000, v96
	v_cndmask_b32_e32 v96, v96, v100, vcc
	v_add_u32_e32 v100, 18, v138
	v_fma_f32 v127, v101, v96, v151
	v_ashrrev_i32_e32 v101, 31, v100
	v_fma_f32 v126, v97, v96, v150
	v_fma_f32 v115, v105, v96, v148
	v_fma_f32 v109, v109, v96, v149
	v_lshl_add_u64 v[96:97], v[100:101], 2, s[76:77]
	v_mov_b32_e32 v96, v186
	v_ashrrev_i32_e32 v105, 31, v104
	s_waitcnt vmcnt(0)
	v_fmamk_f32 v96, v96, 0x3a800000, v147
	v_cmp_gt_f32_e32 vcc, s93, v96
	v_mul_f32_e32 v97, 0x4b800000, v96
	s_nop 0
	v_cndmask_b32_e32 v96, v96, v97, vcc
	v_rsq_f32_e32 v96, v96
	s_nop 0
	v_mul_f32_e32 v97, 0x45800000, v96
	v_cndmask_b32_e32 v96, v96, v97, vcc
	v_fma_f32 v157, v98, v96, v150
	v_fma_f32 v158, v102, v96, v151
	v_fma_f32 v101, v106, v96, v148
	v_fma_f32 v102, v110, v96, v149
	v_lshl_add_u64 v[96:97], v[104:105], 2, s[76:77]
	v_mov_b32_e32 v96, v187
	s_waitcnt vmcnt(0)
	v_fmamk_f32 v96, v96, 0x3a800000, v147
	v_cmp_gt_f32_e32 vcc, s93, v96
	v_mul_f32_e32 v97, 0x4b800000, v96
	s_nop 0
	v_cndmask_b32_e32 v96, v96, v97, vcc
	v_rsq_f32_e32 v96, v96
	s_nop 0
	v_mul_f32_e32 v97, 0x45800000, v96
	v_cndmask_b32_e32 v96, v96, v97, vcc
	v_fma_f32 v161, v99, v96, v150
	v_fma_f32 v162, v103, v96, v151
	v_fma_f32 v103, v107, v96, v148
	v_fma_f32 v105, v111, v96, v149
	v_add_u32_e32 v96, 32, v138
	v_ashrrev_i32_e32 v97, 31, v96
	v_lshl_add_u64 v[98:99], v[96:97], 2, s[76:77]
	v_mov_b32_e32 v97, v188
	s_waitcnt vmcnt(0)
; __device__ __forceinline__ float silu_f(float x) { return x * __builtin_amdgcn_rcpf(1.f + __expf(-x)); }
; __device__ __forceinline__ void norm_fix(f32x4 (&acc)[4][4], const float* rowss, const float* shW, int N, int brow, int bcol,
;                                          int wr, int wc, int fr, int fq) {
;   int mr = brow >> 12;
;   float sw[4];
; #pragma unroll
;   for (int n = 0; n < 4; n++) sw[n] = shW[(size_t)mr * N + bcol + (n >> 1) * 128 + wc * 32 + (n & 1) * 16 + fr];
; #pragma unroll
;   for (int m = 0; m < 4; m++)
; #pragma unroll
;     for (int j = 0; j < 4; j++) {
;       float rs = rsqrtf(rowss[brow + wr * 64 + m * 16 + fq * 4 + j] * (1.f / D) + 1e-6f);
; #pragma unroll
;       for (int n = 0; n < 4; n++) acc[m][n][j] = acc[m][n][j] * rs + sw[n];
;     }
; }
;   __device__ __forceinline__ void operator()(int brow, int bcol, int wr, int wc, int fr, int fq, f32x4 (&acc)[4][4], int split) const {
;     if (rowss && brow < TL) norm_fix(acc, rowss, shW, NGU, brow, bcol, wr, wc, fr, fq);
; #pragma unroll
;     for (int m = 0; m < 4; m++)
; #pragma unroll
;       for (int pr = 0; pr < 2; pr++)
; #pragma unroll
;         for (int j = 0; j < 4; j++) {
;           int row = brow + wr * 64 + m * 16 + fq * 4 + j;
;           int col = (bcol >> 1) + wc * 32 + pr * 16 + fr;
;           float g = acc[m][2 * pr][j], u = acc[m][2 * pr + 1][j];
;           act[(size_t)row * DFF + col] = f2bf(silu_f(g) * u);
	v_fmamk_f32 v97, v97, 0x3a800000, v147
	v_cmp_gt_f32_e32 vcc, s93, v97
	v_mul_f32_e32 v98, 0x4b800000, v97
	s_nop 0
	v_cndmask_b32_e32 v97, v97, v98, vcc
	v_rsq_f32_e32 v97, v97
	s_nop 0
	v_mul_f32_e32 v98, 0x45800000, v97
	v_cndmask_b32_e32 v98, v97, v98, vcc
	v_fma_f32 v106, v80, v98, v150
	v_fma_f32 v107, v84, v98, v151
	v_fma_f32 v97, v88, v98, v148
	v_fma_f32 v92, v92, v98, v149
	v_add_u32_e32 v98, 33, v138
	v_ashrrev_i32_e32 v99, 31, v98
	v_lshl_add_u64 v[110:111], v[98:99], 2, s[76:77]
	v_mov_b32_e32 v80, v189
	v_add_u32_e32 v88, 35, v138
	s_waitcnt vmcnt(0)
	v_fmamk_f32 v80, v80, 0x3a800000, v147
	v_cmp_gt_f32_e32 vcc, s93, v80
	v_mul_f32_e32 v84, 0x4b800000, v80
	s_nop 0
	v_cndmask_b32_e32 v80, v80, v84, vcc
	v_rsq_f32_e32 v80, v80
	s_nop 0
	v_mul_f32_e32 v84, 0x45800000, v80
	v_cndmask_b32_e32 v80, v80, v84, vcc
	v_add_u32_e32 v84, 34, v138
	v_fma_f32 v111, v85, v80, v151
	v_ashrrev_i32_e32 v85, 31, v84
	v_fma_f32 v110, v81, v80, v150
	v_fma_f32 v99, v89, v80, v148
	v_fma_f32 v93, v93, v80, v149
	v_lshl_add_u64 v[80:81], v[84:85], 2, s[76:77]
	v_mov_b32_e32 v80, v190
	v_ashrrev_i32_e32 v89, 31, v88
	s_waitcnt vmcnt(0)
	v_fmamk_f32 v80, v80, 0x3a800000, v147
	v_cmp_gt_f32_e32 vcc, s93, v80
	v_mul_f32_e32 v81, 0x4b800000, v80
	s_nop 0
	v_cndmask_b32_e32 v80, v80, v81, vcc
	v_rsq_f32_e32 v80, v80
	s_nop 0
	v_mul_f32_e32 v81, 0x45800000, v80
	v_cndmask_b32_e32 v80, v80, v81, vcc
	v_fma_f32 v163, v82, v80, v150
	v_fma_f32 v164, v86, v80, v151
	v_fma_f32 v85, v90, v80, v148
	v_fma_f32 v86, v94, v80, v149
	v_lshl_add_u64 v[80:81], v[88:89], 2, s[76:77]
	v_mov_b32_e32 v80, v191
	s_waitcnt vmcnt(0)
	v_fmamk_f32 v80, v80, 0x3a800000, v147
	v_cmp_gt_f32_e32 vcc, s93, v80
	v_mul_f32_e32 v81, 0x4b800000, v80
	s_nop 0
	v_cndmask_b32_e32 v80, v80, v81, vcc
	v_rsq_f32_e32 v80, v80
	s_nop 0
	v_mul_f32_e32 v81, 0x45800000, v80
	v_cndmask_b32_e32 v80, v80, v81, vcc
	v_fma_f32 v166, v83, v80, v150
	v_fma_f32 v167, v87, v80, v151
	v_fma_f32 v87, v91, v80, v148
	v_fma_f32 v89, v95, v80, v149
	v_add_u32_e32 v80, 48, v138
	v_ashrrev_i32_e32 v81, 31, v80
	v_lshl_add_u64 v[82:83], v[80:81], 2, s[76:77]
	v_mov_b32_e32 v81, v192
	s_waitcnt vmcnt(0)
	v_fmamk_f32 v81, v81, 0x3a800000, v147
	v_cmp_gt_f32_e32 vcc, s93, v81
	v_mul_f32_e32 v82, 0x4b800000, v81
	s_nop 0
	v_cndmask_b32_e32 v81, v81, v82, vcc
	v_rsq_f32_e32 v81, v81
	s_nop 0
	v_mul_f32_e32 v82, 0x45800000, v81
	v_cndmask_b32_e32 v82, v81, v82, vcc
	v_fma_f32 v90, v64, v82, v150
	v_fma_f32 v91, v68, v82, v151
	v_fma_f32 v81, v72, v82, v148
	v_fma_f32 v76, v76, v82, v149
	v_add_u32_e32 v82, 49, v138
	v_ashrrev_i32_e32 v83, 31, v82
	v_lshl_add_u64 v[94:95], v[82:83], 2, s[76:77]
	v_mov_b32_e32 v64, v193
	v_add_u32_e32 v72, 51, v138
	s_waitcnt vmcnt(0)
	v_fmamk_f32 v64, v64, 0x3a800000, v147
	v_cmp_gt_f32_e32 vcc, s93, v64
	v_mul_f32_e32 v68, 0x4b800000, v64
	s_nop 0
	v_cndmask_b32_e32 v64, v64, v68, vcc
	v_rsq_f32_e32 v64, v64
	s_nop 0
	v_mul_f32_e32 v68, 0x45800000, v64
	v_cndmask_b32_e32 v64, v64, v68, vcc
	v_add_u32_e32 v68, 50, v138
	v_fma_f32 v95, v69, v64, v151
	v_ashrrev_i32_e32 v69, 31, v68
	v_fma_f32 v94, v65, v64, v150
	v_fma_f32 v83, v73, v64, v148
	v_fma_f32 v77, v77, v64, v149
	v_lshl_add_u64 v[64:65], v[68:69], 2, s[76:77]
	v_mov_b32_e32 v64, v194
	v_ashrrev_i32_e32 v73, 31, v72
	s_waitcnt vmcnt(0)
	v_fmamk_f32 v64, v64, 0x3a800000, v147
	v_cmp_gt_f32_e32 vcc, s93, v64
	v_mul_f32_e32 v65, 0x4b800000, v64
	s_nop 0
	v_cndmask_b32_e32 v64, v64, v65, vcc
	v_rsq_f32_e32 v64, v64
	s_nop 0
	v_mul_f32_e32 v65, 0x45800000, v64
	v_cndmask_b32_e32 v64, v64, v65, vcc
	v_fma_f32 v165, v66, v64, v150
	v_fma_f32 v70, v70, v64, v151
	v_fma_f32 v66, v74, v64, v148
	v_fma_f32 v69, v78, v64, v149
	v_lshl_add_u64 v[64:65], v[72:73], 2, s[76:77]
	v_mov_b32_e32 v64, v195
	s_waitcnt vmcnt(0)
	v_fmamk_f32 v64, v64, 0x3a800000, v147
	v_cmp_gt_f32_e32 vcc, s93, v64
	v_mul_f32_e32 v65, 0x4b800000, v64
	s_nop 0
	v_cndmask_b32_e32 v64, v64, v65, vcc
	v_rsq_f32_e32 v64, v64
	s_nop 0
	v_mul_f32_e32 v65, 0x45800000, v64
	v_cndmask_b32_e32 v64, v64, v65, vcc
	v_fmac_f32_e32 v150, v67, v64
	v_mul_f32_e32 v67, 0xbfb8aa3b, v159
	v_exp_f32_e32 v67, v67
	v_fmac_f32_e32 v151, v71, v64
	v_mul_f32_e32 v71, 0xbfb8aa3b, v155
	v_exp_f32_e32 v71, v71
	v_add_f32_e32 v67, 1.0, v67
	v_rcp_f32_e32 v67, v67
	v_fmac_f32_e32 v148, v75, v64
	v_add_f32_e32 v71, 1.0, v71
	v_rcp_f32_e32 v71, v71
	v_mul_f32_e32 v67, v159, v67
	v_fmac_f32_e32 v149, v79, v64
	v_lshl_add_u64 v[64:65], v[140:141], 1, s[66:67]
	v_mul_f32_e32 v67, v160, v67
	v_cvt_pk_bf16_f32 v67, v67, s0
	v_mad_i64_i32 v[74:75], s[0:1], v138, s94, v[64:65]
	v_mul_f32_e32 v71, v155, v71
	global_store_short v[74:75], v67, off
	v_add_u32_e32 v67, 1, v138
	v_mul_f32_e32 v71, v156, v71
	v_cvt_pk_bf16_f32 v71, v71, s0
	v_mad_i64_i32 v[78:79], s[0:1], v67, s94, v[64:65]
	global_store_short v[78:79], v71, off
	v_mul_f32_e32 v71, 0xbfb8aa3b, v153
	v_exp_f32_e32 v71, v71
	v_add_u32_e32 v67, 2, v138
	v_add_f32_e32 v71, 1.0, v71
	v_rcp_f32_e32 v71, v71
	s_nop 0
	v_mul_f32_e32 v71, v153, v71
	v_mul_f32_e32 v71, v154, v71
	v_cvt_pk_bf16_f32 v71, v71, s0
	v_mad_i64_i32 v[140:141], s[0:1], v67, s94, v[64:65]
	global_store_short v[140:141], v71, off
	v_mul_f32_e32 v71, 0xbfb8aa3b, v122
	v_exp_f32_e32 v71, v71
	v_add_u32_e32 v67, 3, v138
	v_add_f32_e32 v71, 1.0, v71
	v_rcp_f32_e32 v71, v71
	s_nop 0
	v_mul_f32_e32 v71, v122, v71
	v_mul_f32_e32 v71, v119, v71
	v_cvt_pk_bf16_f32 v71, v71, s0
	v_mad_i64_i32 v[154:155], s[0:1], v67, s94, v[64:65]
	v_mul_f32_e32 v67, 0xbfb8aa3b, v139
	v_exp_f32_e32 v67, v67
	global_store_short v[154:155], v71, off
	v_add_f32_e32 v67, 1.0, v67
	v_rcp_f32_e32 v67, v67
; __device__ __forceinline__ float silu_f(float x) { return x * __builtin_amdgcn_rcpf(1.f + __expf(-x)); }
;   __device__ __forceinline__ void operator()(int brow, int bcol, int wr, int wc, int fr, int fq, f32x4 (&acc)[4][4], int split) const {
;     ...
; #pragma unroll
;     for (int m = 0; m < 4; m++)
; #pragma unroll
;       for (int pr = 0; pr < 2; pr++)
; #pragma unroll
;         for (int j = 0; j < 4; j++) {
;           int row = brow + wr * 64 + m * 16 + fq * 4 + j;
;           int col = (bcol >> 1) + wc * 32 + pr * 16 + fr;
;           float g = acc[m][2 * pr][j], u = acc[m][2 * pr + 1][j];
;           act[(size_t)row * DFF + col] = f2bf(silu_f(g) * u);
;         }
	s_nop 0
	v_mul_f32_e32 v67, v139, v67
	v_mul_f32_e32 v67, v152, v67
	v_cvt_pk_bf16_f32 v67, v67, s0
	global_store_short v[74:75], v67, off offset:32
	v_mul_f32_e32 v67, 0xbfb8aa3b, v121
	v_exp_f32_e32 v67, v67
	s_nop 0
	v_add_f32_e32 v67, 1.0, v67
	v_rcp_f32_e32 v67, v67
	s_nop 0
	v_mul_f32_e32 v67, v121, v67
	v_mul_f32_e32 v67, v124, v67
	v_cvt_pk_bf16_f32 v67, v67, s0
	global_store_short v[78:79], v67, off offset:32
	v_mul_f32_e32 v67, 0xbfb8aa3b, v118
	v_exp_f32_e32 v67, v67
	s_nop 0
	v_add_f32_e32 v67, 1.0, v67
	v_rcp_f32_e32 v67, v67
	s_nop 0
	v_mul_f32_e32 v67, v118, v67
	v_mul_f32_e32 v67, v120, v67
	v_cvt_pk_bf16_f32 v67, v67, s0
	global_store_short v[140:141], v67, off offset:32
	v_mul_f32_e32 v67, 0xbfb8aa3b, v116
	v_exp_f32_e32 v67, v67
	s_nop 0
	v_add_f32_e32 v67, 1.0, v67
	v_rcp_f32_e32 v67, v67
	s_nop 0
	v_mul_f32_e32 v67, v116, v67
	v_mul_f32_e32 v67, v117, v67
	v_cvt_pk_bf16_f32 v67, v67, s0
	global_store_short v[154:155], v67, off offset:32
	v_mul_f32_e32 v67, 0xbfb8aa3b, v123
	v_exp_f32_e32 v67, v67
	s_nop 0
	v_add_f32_e32 v67, 1.0, v67
	v_rcp_f32_e32 v67, v67
	s_nop 0
	v_mul_f32_e32 v67, v123, v67
	v_mul_f32_e32 v67, v125, v67
	v_cvt_pk_bf16_f32 v67, v67, s0
	v_mad_i64_i32 v[74:75], s[0:1], v112, s94, v[64:65]
	global_store_short v[74:75], v67, off
	v_mul_f32_e32 v67, 0xbfb8aa3b, v126
	v_exp_f32_e32 v67, v67
	s_nop 0
	v_add_f32_e32 v67, 1.0, v67
	v_rcp_f32_e32 v67, v67
	s_nop 0
	v_mul_f32_e32 v67, v126, v67
	v_mul_f32_e32 v67, v127, v67
	v_cvt_pk_bf16_f32 v67, v67, s0
	v_mad_i64_i32 v[78:79], s[0:1], v114, s94, v[64:65]
	global_store_short v[78:79], v67, off
	v_mul_f32_e32 v67, 0xbfb8aa3b, v157
	v_exp_f32_e32 v67, v67
	s_nop 0
	v_add_f32_e32 v67, 1.0, v67
	v_rcp_f32_e32 v67, v67
	s_nop 0
	v_mul_f32_e32 v67, v157, v67
	v_mul_f32_e32 v67, v158, v67
	v_cvt_pk_bf16_f32 v67, v67, s0
	v_mad_i64_i32 v[116:117], s[0:1], v100, s94, v[64:65]
	global_store_short v[116:117], v67, off
	v_mul_f32_e32 v67, 0xbfb8aa3b, v161
	v_exp_f32_e32 v67, v67
	s_nop 0
	v_add_f32_e32 v67, 1.0, v67
	v_rcp_f32_e32 v67, v67
	s_nop 0
	v_mul_f32_e32 v67, v161, v67
	v_mul_f32_e32 v67, v162, v67
	v_cvt_pk_bf16_f32 v67, v67, s0
	v_mad_i64_i32 v[118:119], s[0:1], v104, s94, v[64:65]
	global_store_short v[118:119], v67, off
	v_mul_f32_e32 v67, 0xbfb8aa3b, v113
	v_exp_f32_e32 v67, v67
	s_nop 0
	v_add_f32_e32 v67, 1.0, v67
	v_rcp_f32_e32 v67, v67
	s_nop 0
	v_mul_f32_e32 v67, v113, v67
	v_mul_f32_e32 v67, v108, v67
	v_cvt_pk_bf16_f32 v67, v67, s0
	global_store_short v[74:75], v67, off offset:32
	v_mul_f32_e32 v67, 0xbfb8aa3b, v115
	v_exp_f32_e32 v67, v67
	s_nop 0
	v_add_f32_e32 v67, 1.0, v67
	v_rcp_f32_e32 v67, v67
	s_nop 0
	v_mul_f32_e32 v67, v115, v67
	v_mul_f32_e32 v67, v109, v67
	v_cvt_pk_bf16_f32 v67, v67, s0
	global_store_short v[78:79], v67, off offset:32
	v_mul_f32_e32 v67, 0xbfb8aa3b, v101
	v_exp_f32_e32 v67, v67
	s_nop 0
	v_add_f32_e32 v67, 1.0, v67
	v_rcp_f32_e32 v67, v67
	s_nop 0
	v_mul_f32_e32 v67, v101, v67
	v_mul_f32_e32 v67, v102, v67
	v_cvt_pk_bf16_f32 v67, v67, s0
	global_store_short v[116:117], v67, off offset:32
	v_mul_f32_e32 v67, 0xbfb8aa3b, v103
	v_exp_f32_e32 v67, v67
	s_nop 0
	v_add_f32_e32 v67, 1.0, v67
	v_rcp_f32_e32 v67, v67
	s_nop 0
	v_mul_f32_e32 v67, v103, v67
	v_mul_f32_e32 v67, v105, v67
	v_cvt_pk_bf16_f32 v67, v67, s0
	global_store_short v[118:119], v67, off offset:32
	v_mul_f32_e32 v67, 0xbfb8aa3b, v106
	v_exp_f32_e32 v67, v67
	s_nop 0
	v_add_f32_e32 v67, 1.0, v67
	v_rcp_f32_e32 v67, v67
	s_nop 0
	v_mul_f32_e32 v67, v106, v67
	v_mul_f32_e32 v67, v107, v67
	v_cvt_pk_bf16_f32 v67, v67, s0
	v_mad_i64_i32 v[74:75], s[0:1], v96, s94, v[64:65]
	global_store_short v[74:75], v67, off
	v_mul_f32_e32 v67, 0xbfb8aa3b, v110
	v_exp_f32_e32 v67, v67
	s_nop 0
	v_add_f32_e32 v67, 1.0, v67
	v_rcp_f32_e32 v67, v67
	s_nop 0
	v_mul_f32_e32 v67, v110, v67
	v_mul_f32_e32 v67, v111, v67
	v_cvt_pk_bf16_f32 v67, v67, s0
	v_mad_i64_i32 v[78:79], s[0:1], v98, s94, v[64:65]
	global_store_short v[78:79], v67, off
	v_mul_f32_e32 v67, 0xbfb8aa3b, v163
	v_exp_f32_e32 v67, v67
	s_nop 0
	v_add_f32_e32 v67, 1.0, v67
	v_rcp_f32_e32 v67, v67
	s_nop 0
	v_mul_f32_e32 v67, v163, v67
	v_mul_f32_e32 v67, v164, v67
	v_cvt_pk_bf16_f32 v67, v67, s0
	v_mad_i64_i32 v[100:101], s[0:1], v84, s94, v[64:65]
	global_store_short v[100:101], v67, off
	v_mul_f32_e32 v67, 0xbfb8aa3b, v166
	v_exp_f32_e32 v67, v67
	s_nop 0
	v_add_f32_e32 v67, 1.0, v67
	v_rcp_f32_e32 v67, v67
	s_nop 0
	v_mul_f32_e32 v67, v166, v67
	v_mul_f32_e32 v67, v167, v67
	v_cvt_pk_bf16_f32 v67, v67, s0
	v_mad_i64_i32 v[102:103], s[0:1], v88, s94, v[64:65]
	global_store_short v[102:103], v67, off
	v_mul_f32_e32 v67, 0xbfb8aa3b, v97
	v_exp_f32_e32 v67, v67
	s_nop 0
	v_add_f32_e32 v67, 1.0, v67
	v_rcp_f32_e32 v67, v67
	s_nop 0
	v_mul_f32_e32 v67, v97, v67
	v_mul_f32_e32 v67, v92, v67
	v_cvt_pk_bf16_f32 v67, v67, s0
	global_store_short v[74:75], v67, off offset:32
	v_mul_f32_e32 v67, 0xbfb8aa3b, v99
	v_exp_f32_e32 v67, v67
	s_nop 0
	v_add_f32_e32 v67, 1.0, v67
	v_rcp_f32_e32 v67, v67
	s_nop 0
	v_mul_f32_e32 v67, v99, v67
	v_mul_f32_e32 v67, v93, v67
	v_cvt_pk_bf16_f32 v67, v67, s0
	global_store_short v[78:79], v67, off offset:32
	v_mul_f32_e32 v67, 0xbfb8aa3b, v85
	v_exp_f32_e32 v67, v67
	s_nop 0
	v_add_f32_e32 v67, 1.0, v67
	v_rcp_f32_e32 v67, v67
	s_nop 0
	v_mul_f32_e32 v67, v85, v67
	v_mul_f32_e32 v67, v86, v67
	v_cvt_pk_bf16_f32 v67, v67, s0
	global_store_short v[100:101], v67, off offset:32
	v_mul_f32_e32 v67, 0xbfb8aa3b, v87
	v_exp_f32_e32 v67, v67
	s_nop 0
	v_add_f32_e32 v67, 1.0, v67
	v_rcp_f32_e32 v67, v67
	s_nop 0
	v_mul_f32_e32 v67, v87, v67
	v_mul_f32_e32 v67, v89, v67
	v_cvt_pk_bf16_f32 v67, v67, s0
; __device__ __forceinline__ float silu_f(float x) { return x * __builtin_amdgcn_rcpf(1.f + __expf(-x)); }
; __device__ __forceinline__ void norm_fix(f32x4 (&acc)[4][4], const float* rowss, const float* shW, int N, int brow, int bcol,
;                                          int wr, int wc, int fr, int fq) {
;   int mr = brow >> 12;
;   float sw[4];
; #pragma unroll
;   for (int n = 0; n < 4; n++) sw[n] = shW[(size_t)mr * N + bcol + (n >> 1) * 128 + wc * 32 + (n & 1) * 16 + fr];
; #pragma unroll
;   for (int m = 0; m < 4; m++)
; #pragma unroll
;     for (int j = 0; j < 4; j++) {
;       float rs = rsqrtf(rowss[brow + wr * 64 + m * 16 + fq * 4 + j] * (1.f / D) + 1e-6f);
; #pragma unroll
;       for (int n = 0; n < 4; n++) acc[m][n][j] = acc[m][n][j] * rs + sw[n];
;     }
; }
;   __device__ __forceinline__ void operator()(int brow, int bcol, int wr, int wc, int fr, int fq, f32x4 (&acc)[4][4], int split) const {
;     if (rowss && brow < TL) norm_fix(acc, rowss, shW, NGU, brow, bcol, wr, wc, fr, fq);
; #pragma unroll
;     for (int m = 0; m < 4; m++)
; #pragma unroll
;       for (int pr = 0; pr < 2; pr++)
; #pragma unroll
;         for (int j = 0; j < 4; j++) {
;           int row = brow + wr * 64 + m * 16 + fq * 4 + j;
;           int col = (bcol >> 1) + wc * 32 + pr * 16 + fr;
;           float g = acc[m][2 * pr][j], u = acc[m][2 * pr + 1][j];
;           act[(size_t)row * DFF + col] = f2bf(silu_f(g) * u);
;         }
	global_store_short v[102:103], v67, off offset:32
	v_mul_f32_e32 v67, 0xbfb8aa3b, v90
	v_exp_f32_e32 v67, v67
	s_nop 0
	v_add_f32_e32 v67, 1.0, v67
	v_rcp_f32_e32 v67, v67
	s_nop 0
	v_mul_f32_e32 v67, v90, v67
	v_mul_f32_e32 v67, v91, v67
	v_cvt_pk_bf16_f32 v67, v67, s0
	v_mad_i64_i32 v[74:75], s[0:1], v80, s94, v[64:65]
	global_store_short v[74:75], v67, off
	v_mul_f32_e32 v67, 0xbfb8aa3b, v94
	v_exp_f32_e32 v67, v67
	s_nop 0
	v_add_f32_e32 v67, 1.0, v67
	v_rcp_f32_e32 v67, v67
	s_nop 0
	v_mul_f32_e32 v67, v94, v67
	v_mul_f32_e32 v67, v95, v67
	v_cvt_pk_bf16_f32 v67, v67, s0
	v_mad_i64_i32 v[78:79], s[0:1], v82, s94, v[64:65]
	global_store_short v[78:79], v67, off
	v_mul_f32_e32 v67, 0xbfb8aa3b, v165
	v_exp_f32_e32 v67, v67
	s_nop 0
	v_add_f32_e32 v67, 1.0, v67
	v_rcp_f32_e32 v67, v67
	s_nop 0
	v_mul_f32_e32 v67, v165, v67
	v_mul_f32_e32 v67, v70, v67
	v_cvt_pk_bf16_f32 v67, v67, s0
	v_mad_i64_i32 v[70:71], s[0:1], v68, s94, v[64:65]
	global_store_short v[70:71], v67, off
	v_mul_f32_e32 v67, 0xbfb8aa3b, v150
	v_exp_f32_e32 v67, v67
	s_nop 0
	v_add_f32_e32 v67, 1.0, v67
	v_rcp_f32_e32 v67, v67
	s_nop 0
	v_mul_f32_e32 v67, v150, v67
	v_mul_f32_e32 v67, v151, v67
	v_cvt_pk_bf16_f32 v67, v67, s0
	v_mad_i64_i32 v[72:73], s[0:1], v72, s94, v[64:65]
	global_store_short v[72:73], v67, off
	v_mul_f32_e32 v67, 0xbfb8aa3b, v81
	v_exp_f32_e32 v67, v67
	s_nop 0
	v_add_f32_e32 v67, 1.0, v67
	v_rcp_f32_e32 v67, v67
	s_nop 0
	v_mul_f32_e32 v67, v81, v67
	v_mul_f32_e32 v67, v76, v67
	v_cvt_pk_bf16_f32 v67, v67, s0
	global_store_short v[74:75], v67, off offset:32
	v_mul_f32_e32 v67, 0xbfb8aa3b, v83
	v_exp_f32_e32 v67, v67
	s_nop 0
	v_add_f32_e32 v67, 1.0, v67
	v_rcp_f32_e32 v67, v67
	s_nop 0
	v_mul_f32_e32 v67, v83, v67
	v_mul_f32_e32 v67, v77, v67
	v_cvt_pk_bf16_f32 v67, v67, s0
	global_store_short v[78:79], v67, off offset:32
	v_mul_f32_e32 v67, 0xbfb8aa3b, v66
	v_exp_f32_e32 v67, v67
	s_nop 0
	v_add_f32_e32 v67, 1.0, v67
	v_rcp_f32_e32 v67, v67
	s_nop 0
	v_mul_f32_e32 v66, v66, v67
	v_mul_f32_e32 v66, v69, v66
	v_cvt_pk_bf16_f32 v66, v66, s0
	global_store_short v[70:71], v66, off offset:32
	v_mul_f32_e32 v66, 0xbfb8aa3b, v148
	v_exp_f32_e32 v66, v66
	s_nop 0
	v_add_f32_e32 v66, 1.0, v66
	v_rcp_f32_e32 v66, v66
	s_nop 0
	v_mul_f32_e32 v66, v148, v66
	v_mul_f32_e32 v66, v149, v66
	v_cvt_pk_bf16_f32 v66, v66, s0
	global_store_short v[72:73], v66, off offset:32
	s_ashr_i32 s0, s56, 12
	s_mul_hi_i32 s1, s0, 0x5800
	s_mulk_i32 s0, 0x5800
	s_add_u32 s0, s33, s0
	s_addc_u32 s1, s45, s1
	s_add_u32 s0, s0, s58
	s_addc_u32 s1, s1, s59
	v_add_u32_e32 v66, s56, v145
	s_add_u32 s0, s0, s92
	v_ashrrev_i32_e32 v67, 31, v66
	s_addc_u32 s1, s1, 0
	v_lshl_add_u64 v[72:73], v[66:67], 2, s[76:77]
	global_load_dword v70, v146, s[0:1]
	global_load_dword v71, v146, s[0:1] offset:64
	global_load_dword v68, v146, s[0:1] offset:512
	global_load_dword v69, v146, s[0:1] offset:576
	global_load_dwordx4 v[184:187], v[72:73], off offset:64
	global_load_dwordx4 v[188:191], v[72:73], off offset:128
	global_load_dwordx4 v[192:195], v[72:73], off offset:192
	global_load_dwordx4 v[76:79], v[72:73], off
	s_waitcnt vmcnt(0)
	v_pk_fma_f32 v[72:73], v[76:77], s[44:45], v[136:137] op_sel_hi:[1,0,0]
	s_nop 0
	v_mul_f32_e32 v67, 0x4b800000, v72
	v_cmp_gt_f32_e64 s[4:5], s93, v72
	v_cmp_gt_f32_e32 vcc, s93, v73
	s_nop 0
	v_cndmask_b32_e64 v67, v72, v67, s[4:5]
	v_rsq_f32_e32 v67, v67
	s_nop 0
	v_mul_f32_e32 v72, 0x45800000, v67
	v_cndmask_b32_e64 v72, v67, v72, s[4:5]
	v_fma_f32 v83, v48, v72, v70
	v_mul_f32_e32 v48, 0x4b800000, v73
	v_cndmask_b32_e32 v48, v73, v48, vcc
	v_rsq_f32_e32 v48, v48
	v_fma_f32 v84, v52, v72, v71
	v_fma_f32 v67, v56, v72, v68
	v_fma_f32 v72, v60, v72, v69
	v_mul_f32_e32 v52, 0x45800000, v48
	v_cndmask_b32_e32 v48, v48, v52, vcc
	v_fma_f32 v75, v49, v48, v70
	v_fma_f32 v76, v53, v48, v71
	v_fma_f32 v57, v57, v48, v68
	v_fma_f32 v60, v61, v48, v69
	v_pk_fma_f32 v[48:49], v[78:79], s[44:45], v[136:137] op_sel_hi:[1,0,0]
	s_nop 0
	v_mul_f32_e32 v52, 0x4b800000, v48
	v_cmp_gt_f32_e64 s[4:5], s93, v48
	v_cmp_gt_f32_e32 vcc, s93, v49
	s_nop 0
	v_cndmask_b32_e64 v48, v48, v52, s[4:5]
	v_rsq_f32_e32 v48, v48
	s_nop 0
	v_mul_f32_e32 v52, 0x45800000, v48
	v_cndmask_b32_e64 v48, v48, v52, s[4:5]
	v_fma_f32 v73, v50, v48, v70
	v_fma_f32 v74, v54, v48, v71
	v_fma_f32 v54, v58, v48, v68
	v_fma_f32 v56, v62, v48, v69
	v_mul_f32_e32 v48, 0x4b800000, v49
	v_cndmask_b32_e32 v48, v49, v48, vcc
	v_rsq_f32_e32 v48, v48
	s_nop 0
	v_mul_f32_e32 v49, 0x45800000, v48
	v_cndmask_b32_e32 v48, v48, v49, vcc
	v_fma_f32 v61, v51, v48, v70
	v_fma_f32 v62, v55, v48, v71
	v_fma_f32 v52, v59, v48, v68
	v_fma_f32 v53, v63, v48, v69
	v_add_u32_e32 v48, 16, v66
	v_ashrrev_i32_e32 v49, 31, v48
	v_lshl_add_u64 v[50:51], v[48:49], 2, s[76:77]
	v_mov_b32_e32 v49, v184
	s_waitcnt vmcnt(0)
	v_fmamk_f32 v49, v49, 0x3a800000, v147
	v_cmp_gt_f32_e32 vcc, s93, v49
	v_mul_f32_e32 v50, 0x4b800000, v49
	s_nop 0
	v_cndmask_b32_e32 v49, v49, v50, vcc
	v_rsq_f32_e32 v49, v49
	s_nop 0
	v_mul_f32_e32 v50, 0x45800000, v49
	v_cndmask_b32_e32 v50, v49, v50, vcc
	v_fma_f32 v55, v32, v50, v70
	v_fma_f32 v58, v36, v50, v71
	v_fma_f32 v49, v40, v50, v68
	v_fma_f32 v44, v44, v50, v69
	v_add_u32_e32 v50, 17, v66
	v_ashrrev_i32_e32 v51, 31, v50
	v_lshl_add_u64 v[78:79], v[50:51], 2, s[76:77]
	v_mov_b32_e32 v32, v185
	v_add_u32_e32 v40, 19, v66
	s_waitcnt vmcnt(0)
; __device__ __forceinline__ void norm_fix(f32x4 (&acc)[4][4], const float* rowss, const float* shW, int N, int brow, int bcol,
;                                          int wr, int wc, int fr, int fq) {
;     ...
;   for (int m = 0; m < 4; m++)
; #pragma unroll
;     for (int j = 0; j < 4; j++) {
;       float rs = rsqrtf(rowss[brow + wr * 64 + m * 16 + fq * 4 + j] * (1.f / D) + 1e-6f);
; #pragma unroll
;       for (int n = 0; n < 4; n++) acc[m][n][j] = acc[m][n][j] * rs + sw[n];
;     }
	v_fmamk_f32 v32, v32, 0x3a800000, v147
	v_cmp_gt_f32_e32 vcc, s93, v32
	v_mul_f32_e32 v36, 0x4b800000, v32
	s_nop 0
	v_cndmask_b32_e32 v32, v32, v36, vcc
	v_rsq_f32_e32 v32, v32
	s_nop 0
	v_mul_f32_e32 v36, 0x45800000, v32
	v_cndmask_b32_e32 v32, v32, v36, vcc
	v_add_u32_e32 v36, 18, v66
	v_fma_f32 v63, v37, v32, v71
	v_ashrrev_i32_e32 v37, 31, v36
	v_fma_f32 v59, v33, v32, v70
	v_fma_f32 v51, v41, v32, v68
	v_fma_f32 v45, v45, v32, v69
	v_lshl_add_u64 v[32:33], v[36:37], 2, s[76:77]
	v_mov_b32_e32 v32, v186
	v_ashrrev_i32_e32 v41, 31, v40
	s_waitcnt vmcnt(0)
	v_fmamk_f32 v32, v32, 0x3a800000, v147
	v_cmp_gt_f32_e32 vcc, s93, v32
	v_mul_f32_e32 v33, 0x4b800000, v32
	s_nop 0
	v_cndmask_b32_e32 v32, v32, v33, vcc
	v_rsq_f32_e32 v32, v32
	s_nop 0
	v_mul_f32_e32 v33, 0x45800000, v32
	v_cndmask_b32_e32 v32, v32, v33, vcc
	v_fma_f32 v77, v34, v32, v70
	v_fma_f32 v78, v38, v32, v71
	v_fma_f32 v37, v42, v32, v68
	v_fma_f32 v38, v46, v32, v69
	v_lshl_add_u64 v[32:33], v[40:41], 2, s[76:77]
	v_mov_b32_e32 v32, v187
	s_waitcnt vmcnt(0)
	v_fmamk_f32 v32, v32, 0x3a800000, v147
	v_cmp_gt_f32_e32 vcc, s93, v32
	v_mul_f32_e32 v33, 0x4b800000, v32
	s_nop 0
	v_cndmask_b32_e32 v32, v32, v33, vcc
	v_rsq_f32_e32 v32, v32
	s_nop 0
	v_mul_f32_e32 v33, 0x45800000, v32
	v_cndmask_b32_e32 v32, v32, v33, vcc
	v_fma_f32 v81, v35, v32, v70
	v_fma_f32 v82, v39, v32, v71
	v_fma_f32 v39, v43, v32, v68
	v_fma_f32 v41, v47, v32, v69
	v_add_u32_e32 v32, 32, v66
	v_ashrrev_i32_e32 v33, 31, v32
	v_lshl_add_u64 v[34:35], v[32:33], 2, s[76:77]
	v_mov_b32_e32 v33, v188
	s_waitcnt vmcnt(0)
	v_fmamk_f32 v33, v33, 0x3a800000, v147
	v_cmp_gt_f32_e32 vcc, s93, v33
	v_mul_f32_e32 v34, 0x4b800000, v33
	s_nop 0
	v_cndmask_b32_e32 v33, v33, v34, vcc
	v_rsq_f32_e32 v33, v33
	s_nop 0
	v_mul_f32_e32 v34, 0x45800000, v33
	v_cndmask_b32_e32 v34, v33, v34, vcc
	v_fma_f32 v42, v16, v34, v70
	v_fma_f32 v43, v20, v34, v71
	v_fma_f32 v33, v24, v34, v68
	v_fma_f32 v28, v28, v34, v69
	v_add_u32_e32 v34, 33, v66
	v_ashrrev_i32_e32 v35, 31, v34
	v_lshl_add_u64 v[46:47], v[34:35], 2, s[76:77]
	v_mov_b32_e32 v16, v189
	v_add_u32_e32 v24, 35, v66
	s_waitcnt vmcnt(0)
	v_fmamk_f32 v16, v16, 0x3a800000, v147
	v_cmp_gt_f32_e32 vcc, s93, v16
	v_mul_f32_e32 v20, 0x4b800000, v16
	s_nop 0
	v_cndmask_b32_e32 v16, v16, v20, vcc
	v_rsq_f32_e32 v16, v16
	s_nop 0
	v_mul_f32_e32 v20, 0x45800000, v16
	v_cndmask_b32_e32 v16, v16, v20, vcc
	v_fma_f32 v46, v17, v16, v70
	v_fma_f32 v47, v21, v16, v71
	v_fma_f32 v35, v25, v16, v68
	v_fma_f32 v29, v29, v16, v69
	v_add_u32_e32 v16, 34, v66
	v_ashrrev_i32_e32 v17, 31, v16
	v_lshl_add_u64 v[20:21], v[16:17], 2, s[76:77]
	v_mov_b32_e32 v17, v190
	v_ashrrev_i32_e32 v25, 31, v24
	s_waitcnt vmcnt(0)
	v_fmamk_f32 v17, v17, 0x3a800000, v147
	v_cmp_gt_f32_e32 vcc, s93, v17
	v_mul_f32_e32 v20, 0x4b800000, v17
	s_nop 0
	v_cndmask_b32_e32 v17, v17, v20, vcc
	v_rsq_f32_e32 v17, v17
	s_nop 0
	v_mul_f32_e32 v20, 0x45800000, v17
	v_cndmask_b32_e32 v20, v17, v20, vcc
	v_fma_f32 v79, v18, v20, v70
	v_fma_f32 v80, v22, v20, v71
	v_fma_f32 v17, v26, v20, v68
	v_fma_f32 v22, v30, v20, v69
	v_lshl_add_u64 v[20:21], v[24:25], 2, s[76:77]
	v_mov_b32_e32 v18, v191
	s_waitcnt vmcnt(0)
	v_fmamk_f32 v18, v18, 0x3a800000, v147
	v_cmp_gt_f32_e32 vcc, s93, v18
	v_mul_f32_e32 v20, 0x4b800000, v18
	s_nop 0
	v_cndmask_b32_e32 v18, v18, v20, vcc
	v_rsq_f32_e32 v18, v18
	s_nop 0
	v_mul_f32_e32 v20, 0x45800000, v18
	v_cndmask_b32_e32 v18, v18, v20, vcc
	v_fma_f32 v85, v19, v18, v70
	v_fma_f32 v86, v23, v18, v71
	v_fma_f32 v23, v27, v18, v68
	v_fma_f32 v25, v31, v18, v69
	v_add_u32_e32 v18, 48, v66
	v_ashrrev_i32_e32 v19, 31, v18
	v_lshl_add_u64 v[20:21], v[18:19], 2, s[76:77]
	v_mov_b32_e32 v19, v192
	s_waitcnt vmcnt(0)
	v_fmamk_f32 v19, v19, 0x3a800000, v147
	v_cmp_gt_f32_e32 vcc, s93, v19
	v_mul_f32_e32 v20, 0x4b800000, v19
	s_nop 0
	v_cndmask_b32_e32 v19, v19, v20, vcc
	v_rsq_f32_e32 v19, v19
	s_nop 0
	v_mul_f32_e32 v20, 0x45800000, v19
	v_cndmask_b32_e32 v20, v19, v20, vcc
	v_fma_f32 v19, v0, v20, v70
	v_fma_f32 v26, v4, v20, v71
	v_fma_f32 v8, v8, v20, v68
	v_fma_f32 v12, v12, v20, v69
	v_add_u32_e32 v20, 49, v66
	v_ashrrev_i32_e32 v21, 31, v20
	v_lshl_add_u64 v[30:31], v[20:21], 2, s[76:77]
	v_mov_b32_e32 v0, v193
	s_waitcnt vmcnt(0)
	v_fmamk_f32 v0, v0, 0x3a800000, v147
	v_cmp_gt_f32_e32 vcc, s93, v0
	v_mul_f32_e32 v4, 0x4b800000, v0
	s_nop 0
	v_cndmask_b32_e32 v0, v0, v4, vcc
	v_rsq_f32_e32 v0, v0
	s_nop 0
	v_mul_f32_e32 v4, 0x45800000, v0
	v_cndmask_b32_e32 v0, v0, v4, vcc
	v_fma_f32 v21, v1, v0, v70
	v_fma_f32 v27, v5, v0, v71
	v_fma_f32 v9, v9, v0, v68
	v_fma_f32 v13, v13, v0, v69
	v_add_u32_e32 v0, 50, v66
	v_ashrrev_i32_e32 v1, 31, v0
	v_lshl_add_u64 v[4:5], v[0:1], 2, s[76:77]
	v_mov_b32_e32 v1, v194
	s_waitcnt vmcnt(0)
	v_fmamk_f32 v1, v1, 0x3a800000, v147
	v_cmp_gt_f32_e32 vcc, s93, v1
	v_mul_f32_e32 v4, 0x4b800000, v1
	s_nop 0
	v_cndmask_b32_e32 v1, v1, v4, vcc
	v_rsq_f32_e32 v1, v1
	s_nop 0
	v_mul_f32_e32 v4, 0x45800000, v1
	v_cndmask_b32_e32 v4, v1, v4, vcc
	v_fma_f32 v30, v2, v4, v70
	v_fma_f32 v6, v6, v4, v71
	v_fma_f32 v1, v10, v4, v68
	v_fma_f32 v2, v14, v4, v69
	v_add_u32_e32 v4, 51, v66
	v_ashrrev_i32_e32 v5, 31, v4
	v_lshl_add_u64 v[88:89], v[4:5], 2, s[76:77]
	v_mov_b32_e32 v5, v195
	s_waitcnt vmcnt(0)
; __device__ __forceinline__ float silu_f(float x) { return x * __builtin_amdgcn_rcpf(1.f + __expf(-x)); }
; __device__ __forceinline__ void norm_fix(f32x4 (&acc)[4][4], const float* rowss, const float* shW, int N, int brow, int bcol,
;                                          int wr, int wc, int fr, int fq) {
;     ...
;   for (int m = 0; m < 4; m++)
; #pragma unroll
;     for (int j = 0; j < 4; j++) {
;       float rs = rsqrtf(rowss[brow + wr * 64 + m * 16 + fq * 4 + j] * (1.f / D) + 1e-6f);
; #pragma unroll
;       for (int n = 0; n < 4; n++) acc[m][n][j] = acc[m][n][j] * rs + sw[n];
;     }
; }
;   __device__ __forceinline__ void operator()(int brow, int bcol, int wr, int wc, int fr, int fq, f32x4 (&acc)[4][4], int split) const {
;     if (rowss && brow < TL) norm_fix(acc, rowss, shW, NGU, brow, bcol, wr, wc, fr, fq);
; #pragma unroll
;     for (int m = 0; m < 4; m++)
; #pragma unroll
;       for (int pr = 0; pr < 2; pr++)
; #pragma unroll
;         for (int j = 0; j < 4; j++) {
;           int row = brow + wr * 64 + m * 16 + fq * 4 + j;
;           int col = (bcol >> 1) + wc * 32 + pr * 16 + fr;
;           float g = acc[m][2 * pr][j], u = acc[m][2 * pr + 1][j];
;           act[(size_t)row * DFF + col] = f2bf(silu_f(g) * u);
;         }
	v_fmamk_f32 v5, v5, 0x3a800000, v147
	v_cmp_gt_f32_e32 vcc, s93, v5
	v_mul_f32_e32 v10, 0x4b800000, v5
	s_nop 0
	v_cndmask_b32_e32 v5, v5, v10, vcc
	v_rsq_f32_e32 v5, v5
	s_nop 0
	v_mul_f32_e32 v10, 0x45800000, v5
	v_cndmask_b32_e32 v5, v5, v10, vcc
	v_fmac_f32_e32 v70, v3, v5
	v_mul_f32_e32 v3, 0xbfb8aa3b, v83
	v_exp_f32_e32 v3, v3
	v_fmac_f32_e32 v71, v7, v5
	v_fmac_f32_e32 v68, v11, v5
	v_fmac_f32_e32 v69, v15, v5
	v_mul_f32_e32 v5, 0xbfb8aa3b, v75
	v_exp_f32_e32 v5, v5
	v_add_f32_e32 v3, 1.0, v3
	v_rcp_f32_e32 v3, v3
	v_add_f32_e32 v5, 1.0, v5
	v_rcp_f32_e32 v5, v5
	v_mul_f32_e32 v3, v83, v3
	v_mul_f32_e32 v3, v84, v3
	v_cvt_pk_bf16_f32 v3, v3, s0
	v_mad_i64_i32 v[10:11], s[0:1], v66, s94, v[64:65]
	v_mul_f32_e32 v5, v75, v5
	global_store_short v[10:11], v3, off
	v_add_u32_e32 v3, 1, v66
	v_mul_f32_e32 v5, v76, v5
	v_cvt_pk_bf16_f32 v5, v5, s0
	v_mad_i64_i32 v[14:15], s[0:1], v3, s94, v[64:65]
	global_store_short v[14:15], v5, off
	v_mul_f32_e32 v5, 0xbfb8aa3b, v73
	v_exp_f32_e32 v5, v5
	v_add_u32_e32 v3, 2, v66
	v_add_f32_e32 v5, 1.0, v5
	v_rcp_f32_e32 v5, v5
	s_nop 0
	v_mul_f32_e32 v5, v73, v5
	v_mul_f32_e32 v5, v74, v5
	v_cvt_pk_bf16_f32 v5, v5, s0
	v_mad_i64_i32 v[74:75], s[0:1], v3, s94, v[64:65]
	global_store_short v[74:75], v5, off
	v_mul_f32_e32 v5, 0xbfb8aa3b, v61
	v_exp_f32_e32 v5, v5
	v_add_u32_e32 v3, 3, v66
	v_add_f32_e32 v5, 1.0, v5
	v_rcp_f32_e32 v5, v5
	s_nop 0
	v_mul_f32_e32 v5, v61, v5
	v_mul_f32_e32 v5, v62, v5
	v_cvt_pk_bf16_f32 v5, v5, s0
	v_mad_i64_i32 v[88:89], s[0:1], v3, s94, v[64:65]
	v_mul_f32_e32 v3, 0xbfb8aa3b, v67
	v_exp_f32_e32 v3, v3
	global_store_short v[88:89], v5, off
	v_add_f32_e32 v3, 1.0, v3
	v_rcp_f32_e32 v3, v3
	s_nop 0
	v_mul_f32_e32 v3, v67, v3
	v_mul_f32_e32 v3, v72, v3
	v_cvt_pk_bf16_f32 v3, v3, s0
	global_store_short v[10:11], v3, off offset:32
	v_mul_f32_e32 v3, 0xbfb8aa3b, v57
	v_exp_f32_e32 v3, v3
	s_nop 0
	v_add_f32_e32 v3, 1.0, v3
	v_rcp_f32_e32 v3, v3
	s_nop 0
	v_mul_f32_e32 v3, v57, v3
	v_mul_f32_e32 v3, v60, v3
	v_cvt_pk_bf16_f32 v3, v3, s0
	global_store_short v[14:15], v3, off offset:32
	v_mul_f32_e32 v3, 0xbfb8aa3b, v54
	v_exp_f32_e32 v3, v3
	s_nop 0
	v_add_f32_e32 v3, 1.0, v3
	v_rcp_f32_e32 v3, v3
	s_nop 0
	v_mul_f32_e32 v3, v54, v3
	v_mul_f32_e32 v3, v56, v3
	v_cvt_pk_bf16_f32 v3, v3, s0
	global_store_short v[74:75], v3, off offset:32
	v_mul_f32_e32 v3, 0xbfb8aa3b, v52
	v_exp_f32_e32 v3, v3
	s_nop 0
	v_add_f32_e32 v3, 1.0, v3
	v_rcp_f32_e32 v3, v3
	s_nop 0
	v_mul_f32_e32 v3, v52, v3
	v_mul_f32_e32 v3, v53, v3
	v_cvt_pk_bf16_f32 v3, v3, s0
	global_store_short v[88:89], v3, off offset:32
	v_mul_f32_e32 v3, 0xbfb8aa3b, v55
	v_exp_f32_e32 v3, v3
	s_nop 0
	v_add_f32_e32 v3, 1.0, v3
	v_rcp_f32_e32 v3, v3
	s_nop 0
	v_mul_f32_e32 v3, v55, v3
	v_mul_f32_e32 v3, v58, v3
	v_cvt_pk_bf16_f32 v3, v3, s0
	v_mad_i64_i32 v[10:11], s[0:1], v48, s94, v[64:65]
	global_store_short v[10:11], v3, off
	v_mul_f32_e32 v3, 0xbfb8aa3b, v59
	v_exp_f32_e32 v3, v3
	s_nop 0
	v_add_f32_e32 v3, 1.0, v3
	v_rcp_f32_e32 v3, v3
	s_nop 0
	v_mul_f32_e32 v3, v59, v3
	v_mul_f32_e32 v3, v63, v3
	v_cvt_pk_bf16_f32 v3, v3, s0
	v_mad_i64_i32 v[14:15], s[0:1], v50, s94, v[64:65]
	global_store_short v[14:15], v3, off
	v_mul_f32_e32 v3, 0xbfb8aa3b, v77
	v_exp_f32_e32 v3, v3
	s_nop 0
	v_add_f32_e32 v3, 1.0, v3
	v_rcp_f32_e32 v3, v3
	s_nop 0
	v_mul_f32_e32 v3, v77, v3
	v_mul_f32_e32 v3, v78, v3
	v_cvt_pk_bf16_f32 v3, v3, s0
	v_mad_i64_i32 v[52:53], s[0:1], v36, s94, v[64:65]
	global_store_short v[52:53], v3, off
	v_mul_f32_e32 v3, 0xbfb8aa3b, v81
	v_exp_f32_e32 v3, v3
	s_nop 0
	v_add_f32_e32 v3, 1.0, v3
	v_rcp_f32_e32 v3, v3
	s_nop 0
	v_mul_f32_e32 v3, v81, v3
	v_mul_f32_e32 v3, v82, v3
	v_cvt_pk_bf16_f32 v3, v3, s0
	v_mad_i64_i32 v[54:55], s[0:1], v40, s94, v[64:65]
	global_store_short v[54:55], v3, off
	v_mul_f32_e32 v3, 0xbfb8aa3b, v49
	v_exp_f32_e32 v3, v3
	s_nop 0
	v_add_f32_e32 v3, 1.0, v3
	v_rcp_f32_e32 v3, v3
	s_nop 0
	v_mul_f32_e32 v3, v49, v3
	v_mul_f32_e32 v3, v44, v3
	v_cvt_pk_bf16_f32 v3, v3, s0
	global_store_short v[10:11], v3, off offset:32
	v_mul_f32_e32 v3, 0xbfb8aa3b, v51
	v_exp_f32_e32 v3, v3
	s_nop 0
	v_add_f32_e32 v3, 1.0, v3
	v_rcp_f32_e32 v3, v3
	s_nop 0
	v_mul_f32_e32 v3, v51, v3
	v_mul_f32_e32 v3, v45, v3
	v_cvt_pk_bf16_f32 v3, v3, s0
	global_store_short v[14:15], v3, off offset:32
	v_mul_f32_e32 v3, 0xbfb8aa3b, v37
	v_exp_f32_e32 v3, v3
	s_nop 0
	v_add_f32_e32 v3, 1.0, v3
	v_rcp_f32_e32 v3, v3
	s_nop 0
	v_mul_f32_e32 v3, v37, v3
	v_mul_f32_e32 v3, v38, v3
	v_cvt_pk_bf16_f32 v3, v3, s0
	global_store_short v[52:53], v3, off offset:32
	v_mul_f32_e32 v3, 0xbfb8aa3b, v39
	v_exp_f32_e32 v3, v3
	s_nop 0
	v_add_f32_e32 v3, 1.0, v3
; __device__ __forceinline__ float silu_f(float x) { return x * __builtin_amdgcn_rcpf(1.f + __expf(-x)); }
;   __device__ __forceinline__ void operator()(int brow, int bcol, int wr, int wc, int fr, int fq, f32x4 (&acc)[4][4], int split) const {
;     ...
; #pragma unroll
;     for (int m = 0; m < 4; m++)
; #pragma unroll
;       for (int pr = 0; pr < 2; pr++)
; #pragma unroll
;         for (int j = 0; j < 4; j++) {
;           int row = brow + wr * 64 + m * 16 + fq * 4 + j;
;           int col = (bcol >> 1) + wc * 32 + pr * 16 + fr;
;           float g = acc[m][2 * pr][j], u = acc[m][2 * pr + 1][j];
;           act[(size_t)row * DFF + col] = f2bf(silu_f(g) * u);
;         }
	v_rcp_f32_e32 v3, v3
	s_nop 0
	v_mul_f32_e32 v3, v39, v3
	v_mul_f32_e32 v3, v41, v3
	v_cvt_pk_bf16_f32 v3, v3, s0
	global_store_short v[54:55], v3, off offset:32
	v_mul_f32_e32 v3, 0xbfb8aa3b, v42
	v_exp_f32_e32 v3, v3
	s_nop 0
	v_add_f32_e32 v3, 1.0, v3
	v_rcp_f32_e32 v3, v3
	s_nop 0
	v_mul_f32_e32 v3, v42, v3
	v_mul_f32_e32 v3, v43, v3
	v_cvt_pk_bf16_f32 v3, v3, s0
	v_mad_i64_i32 v[10:11], s[0:1], v32, s94, v[64:65]
	global_store_short v[10:11], v3, off
	v_mul_f32_e32 v3, 0xbfb8aa3b, v46
	v_exp_f32_e32 v3, v3
	s_nop 0
	v_add_f32_e32 v3, 1.0, v3
	v_rcp_f32_e32 v3, v3
	s_nop 0
	v_mul_f32_e32 v3, v46, v3
	v_mul_f32_e32 v3, v47, v3
	v_cvt_pk_bf16_f32 v3, v3, s0
	v_mad_i64_i32 v[14:15], s[0:1], v34, s94, v[64:65]
	global_store_short v[14:15], v3, off
	v_mul_f32_e32 v3, 0xbfb8aa3b, v79
	v_exp_f32_e32 v3, v3
	s_nop 0
	v_add_f32_e32 v3, 1.0, v3
	v_rcp_f32_e32 v3, v3
	s_nop 0
	v_mul_f32_e32 v3, v79, v3
	v_mul_f32_e32 v3, v80, v3
	v_cvt_pk_bf16_f32 v3, v3, s0
	v_mad_i64_i32 v[36:37], s[0:1], v16, s94, v[64:65]
	global_store_short v[36:37], v3, off
	v_mul_f32_e32 v3, 0xbfb8aa3b, v85
	v_exp_f32_e32 v3, v3
	s_nop 0
	v_add_f32_e32 v3, 1.0, v3
	v_rcp_f32_e32 v3, v3
	s_nop 0
	v_mul_f32_e32 v3, v85, v3
	v_mul_f32_e32 v3, v86, v3
	v_cvt_pk_bf16_f32 v3, v3, s0
	v_mad_i64_i32 v[38:39], s[0:1], v24, s94, v[64:65]
	global_store_short v[38:39], v3, off
	v_mul_f32_e32 v3, 0xbfb8aa3b, v33
	v_exp_f32_e32 v3, v3
	s_nop 0
	v_add_f32_e32 v3, 1.0, v3
	v_rcp_f32_e32 v3, v3
	s_nop 0
	v_mul_f32_e32 v3, v33, v3
	v_mul_f32_e32 v3, v28, v3
	v_cvt_pk_bf16_f32 v3, v3, s0
	global_store_short v[10:11], v3, off offset:32
	v_mul_f32_e32 v3, 0xbfb8aa3b, v35
	v_exp_f32_e32 v3, v3
	s_nop 0
	v_add_f32_e32 v3, 1.0, v3
	v_rcp_f32_e32 v3, v3
	s_nop 0
	v_mul_f32_e32 v3, v35, v3
	v_mul_f32_e32 v3, v29, v3
	v_cvt_pk_bf16_f32 v3, v3, s0
	global_store_short v[14:15], v3, off offset:32
	v_mul_f32_e32 v3, 0xbfb8aa3b, v17
	v_exp_f32_e32 v3, v3
	s_nop 0
	v_add_f32_e32 v3, 1.0, v3
	v_rcp_f32_e32 v3, v3
	s_nop 0
	v_mul_f32_e32 v3, v17, v3
	v_mul_f32_e32 v3, v22, v3
	v_cvt_pk_bf16_f32 v3, v3, s0
	global_store_short v[36:37], v3, off offset:32
	v_mul_f32_e32 v3, 0xbfb8aa3b, v23
	v_exp_f32_e32 v3, v3
	s_nop 0
	v_add_f32_e32 v3, 1.0, v3
	v_rcp_f32_e32 v3, v3
	s_nop 0
	v_mul_f32_e32 v3, v23, v3
	v_mul_f32_e32 v3, v25, v3
	v_cvt_pk_bf16_f32 v3, v3, s0
	global_store_short v[38:39], v3, off offset:32
	v_mul_f32_e32 v3, 0xbfb8aa3b, v19
	v_exp_f32_e32 v3, v3
	s_nop 0
	v_add_f32_e32 v3, 1.0, v3
	v_rcp_f32_e32 v3, v3
	s_nop 0
	v_mul_f32_e32 v3, v19, v3
	v_mul_f32_e32 v3, v26, v3
	v_cvt_pk_bf16_f32 v3, v3, s0
	v_mad_i64_i32 v[10:11], s[0:1], v18, s94, v[64:65]
	global_store_short v[10:11], v3, off
	v_mul_f32_e32 v3, 0xbfb8aa3b, v21
	v_exp_f32_e32 v3, v3
	s_nop 0
	v_add_f32_e32 v3, 1.0, v3
	v_rcp_f32_e32 v3, v3
	s_nop 0
	v_mul_f32_e32 v3, v21, v3
	v_mul_f32_e32 v3, v27, v3
	v_cvt_pk_bf16_f32 v3, v3, s0
	v_mad_i64_i32 v[14:15], s[0:1], v20, s94, v[64:65]
	global_store_short v[14:15], v3, off
	v_mul_f32_e32 v3, 0xbfb8aa3b, v30
	v_exp_f32_e32 v3, v3
	s_nop 0
	v_add_f32_e32 v3, 1.0, v3
	v_rcp_f32_e32 v3, v3
	s_nop 0
	v_mul_f32_e32 v3, v30, v3
	v_mul_f32_e32 v3, v6, v3
	v_cvt_pk_bf16_f32 v3, v3, s0
	v_mad_i64_i32 v[6:7], s[0:1], v0, s94, v[64:65]
	v_mul_f32_e32 v0, 0xbfb8aa3b, v70
	v_exp_f32_e32 v0, v0
	global_store_short v[6:7], v3, off
	v_add_f32_e32 v0, 1.0, v0
	v_rcp_f32_e32 v0, v0
	s_nop 0
	v_mul_f32_e32 v0, v70, v0
	v_mul_f32_e32 v0, v71, v0
	v_cvt_pk_bf16_f32 v0, v0, s0
	v_mad_i64_i32 v[4:5], s[0:1], v4, s94, v[64:65]
	global_store_short v[4:5], v0, off
	v_mul_f32_e32 v0, 0xbfb8aa3b, v8
	v_exp_f32_e32 v0, v0
	s_nop 0
	v_add_f32_e32 v0, 1.0, v0
	v_rcp_f32_e32 v0, v0
	s_nop 0
	v_mul_f32_e32 v0, v8, v0
	v_mul_f32_e32 v0, v12, v0
	v_cvt_pk_bf16_f32 v0, v0, s0
	global_store_short v[10:11], v0, off offset:32
	v_mul_f32_e32 v0, 0xbfb8aa3b, v9
	v_exp_f32_e32 v0, v0
	s_nop 0
	v_add_f32_e32 v0, 1.0, v0
	v_rcp_f32_e32 v0, v0
	s_nop 0
	v_mul_f32_e32 v0, v9, v0
	v_mul_f32_e32 v0, v13, v0
	v_cvt_pk_bf16_f32 v0, v0, s0
	global_store_short v[14:15], v0, off offset:32
	v_mul_f32_e32 v0, 0xbfb8aa3b, v1
	v_exp_f32_e32 v0, v0
	s_nop 0
	v_add_f32_e32 v0, 1.0, v0
	v_rcp_f32_e32 v0, v0
	s_nop 0
	v_mul_f32_e32 v0, v1, v0
	v_mul_f32_e32 v0, v2, v0
	v_cvt_pk_bf16_f32 v0, v0, s0
	global_store_short v[6:7], v0, off offset:32
	v_mul_f32_e32 v0, 0xbfb8aa3b, v68
	v_exp_f32_e32 v0, v0
	s_nop 0
	v_add_f32_e32 v0, 1.0, v0
	v_rcp_f32_e32 v0, v0
	s_nop 0
	v_mul_f32_e32 v0, v68, v0
	v_mul_f32_e32 v0, v69, v0
	v_cvt_pk_bf16_f32 v0, v0, s0
	global_store_short v[4:5], v0, off offset:32
	s_andn2_b64 vcc, exec, s[50:51]
	s_mov_b32 s58, s52
	s_mov_b32 s4, s54
	s_cbranch_vccz .LBB0_1332
